# split128 + coalesced sk_tile in P2 and P12
# speedup vs baseline: 1.0130x; 1.0130x over previous
; #define LAS __attribute__((address_space(3)))
; __device__ __forceinline__ unsigned long long rt() { return __builtin_amdgcn_s_memrealtime(); }
; __device__ __forceinline__ unsigned cvtpk(float lo, float hi) { f32x2_t v = {lo, hi}; bf16x2_t b = __builtin_convertvector(v, bf16x2_t); return __builtin_bit_cast(unsigned, b); }
; #define MFMA16(a, b, c) __builtin_amdgcn_mfma_f32_16x16x32_bf16((a), (b), (c), 0, 0, 0)
; __device__ __forceinline__ void sk_tile(LAS unsigned char* lds, const bf16* A, int lda, const bf16* Wt, int K, int r0, int c0, int tid, int wave, int lane) {
;     const int r16 = lane & 15, kg = lane >> 4;
;     const int ksl = K >> 3, k0 = wave * ksl;
;     const bf16* ap = A + (size_t)(r0 + r16) * lda + k0 + 8 * kg;
;     const bf16* bp = Wt + (size_t)(c0 + r16) * K + k0 + 8 * kg;
;     f32x4 acc[2][4];
; #pragma unroll
;     for (int m = 0; m < 2; ++m)
; #pragma unroll
;         for (int j = 0; j < 4; ++j) acc[m][j] = (f32x4){0.f, 0.f, 0.f, 0.f};
; #pragma unroll 2
;     for (int ks = 0; ks < (ksl >> 5); ++ks) {
;         bf16x8 af[2], bf[4];
; #pragma unroll
;         for (int m = 0; m < 2; ++m) af[m] = *(const bf16x8*)(ap + (size_t)(16 * m) * lda + 32 * ks);
; #pragma unroll
;         for (int j = 0; j < 4; ++j) bf[j] = *(const bf16x8*)(bp + (size_t)(16 * j) * K + 32 * ks);
; #pragma unroll
;         for (int m = 0; m < 2; ++m)
; #pragma unroll
;             for (int j = 0; j < 4; ++j) acc[m][j] = MFMA16(af[m], bf[j], acc[m][j]);
;     }
; __device__ __forceinline__ void sk_gemm_y(LAS unsigned char* lds, const bf16* A, int lda, const bf16* Wt, int K, bf16* Y, int tid, int wave, int lane) {
;     for (int item = blockIdx.x; item < 256; item += gridDim.x) {
;         const int rt = item >> 4, ct = item & 15;
;         sk_tile(lds, A, lda, Wt, K, MP + 32 * rt, 64 * ct, tid, wave, lane);
;         const f32x4 v = ((const LAS f32x4*)(lds + 65536))[tid];
;         *(uint2*)(Y + (size_t)(MP + 32 * rt + (tid >> 4)) * D + 64 * ct + 4 * (tid & 15)) = make_uint2(cvtpk(v[0], v[1]), cvtpk(v[2], v[3]));
.LBB0_1670:
	s_and_b32 s7, s2, 0xffffffe0
	s_and_b32 s8, s0, 0x3c0
	s_addk_i32 s7, 0x4000
	v_lshrrev_b32_e32 v33, 4, v162
	v_and_b32_e32 v32, 3, v162
	v_sub_u32_e32 v33, 0, v33
	v_xor_b32_e32 v32, v32, v33
	v_and_b32_e32 v32, 3, v32
	v_lshlrev_b32_e32 v32, 4, v32
	v_and_b32_e32 v33, 48, v162
	v_sub_u32_e32 v32, v32, v33
	v_ashrrev_i32_e32 v33, 31, v32
	v_lshrrev_b32_e32 v34, 2, v162
	v_readlane_b32 s98, v254, 34
	s_nop 3
	s_lshl_b32 s98, s98, 14
	v_lshl_add_u32 v36, v162, 4, s98
	v_and_b32_e32 v37, 15, v162
	v_lshrrev_b32_e32 v35, 2, v37
	v_sub_u32_e32 v35, 0, v35
	v_lshlrev_b32_e32 v37, 6, v37
	v_lshrrev_b32_e32 v38, 4, v162
	v_xor_b32_e32 v35, v35, v38
	v_and_b32_e32 v35, 3, v35
	v_lshl_add_u32 v37, v35, 4, v37
	v_add_u32_e32 v37, s98, v37
	v_or_b32_e32 v38, s8, v34
	v_or_b32_e32 v39, s7, v34
	v_mul_u32_u24_e32 v38, 0xb00, v38
	v_mad_i64_i32 v[56:57], s[10:11], v39, s6, v[6:7]
	v_lshlrev_b32_e32 v4, 1, v38
	s_mov_b64 s[98:99], 0x16000
	s_mov_b64 s[100:101], 0x2c000
	v_lshl_add_u64 v[60:61], v[8:9], 0, v[4:5]
	v_lshl_add_u64 v[56:57], v[56:57], 0, v[32:33]
	v_lshl_add_u64 v[60:61], v[60:61], 0, v[32:33]
	v_lshl_add_u64 v[58:59], v[56:57], 0, s[98:99]
	v_lshl_add_u64 v[62:63], v[60:61], 0, s[98:99]
	v_lshl_add_u64 v[64:65], v[60:61], 0, s[100:101]
	s_mov_b64 s[100:101], 0x42000
	v_lshl_add_u64 v[66:67], v[60:61], 0, s[100:101]
	s_lshl_b32 s8, s8, 1
	v_or_b32_e32 v32, s7, v186
	v_ashrrev_i32_e32 v33, 31, v32
	v_lshlrev_b64 v[32:33], 11, v[32:33]
	v_lshl_add_u64 v[32:33], s[56:57], 0, v[32:33]
	v_lshl_add_u64 v[32:33], v[32:33], 0, s[8:9]
	v_lshl_add_u64 v[52:53], v[32:33], 0, v[10:11]
	s_add_i32 s86, s86, s87
	s_add_i32 s0, s0, s1
	s_add_i32 s2, s2, s3
	s_cmpk_lt_i32 s86, 0x100
	global_load_dwordx4 v[116:119], v[56:57], off
	global_load_dwordx4 v[120:123], v[58:59], off
	global_load_dwordx4 v[124:127], v[60:61], off
	global_load_dwordx4 v[128:131], v[62:63], off
	global_load_dwordx4 v[132:135], v[64:65], off
	global_load_dwordx4 v[136:139], v[66:67], off
	global_load_dwordx4 v[140:143], v[56:57], off offset:64
	global_load_dwordx4 v[144:147], v[58:59], off offset:64
	global_load_dwordx4 v[148:151], v[60:61], off offset:64
	global_load_dwordx4 v[152:155], v[62:63], off offset:64
	global_load_dwordx4 v[156:159], v[64:65], off offset:64
	global_load_dwordx4 v[168:171], v[66:67], off offset:64
	global_load_dwordx4 v[172:175], v[56:57], off offset:128
	global_load_dwordx4 v[176:179], v[58:59], off offset:128
	global_load_dwordx4 v[180:183], v[60:61], off offset:128
	global_load_dwordx4 v[192:195], v[62:63], off offset:128
	global_load_dwordx4 v[196:199], v[64:65], off offset:128
	global_load_dwordx4 v[200:203], v[66:67], off offset:128
	global_load_dwordx4 v[204:207], v[56:57], off offset:192
	global_load_dwordx4 v[208:211], v[58:59], off offset:192
	global_load_dwordx4 v[212:215], v[60:61], off offset:192
	global_load_dwordx4 v[216:219], v[62:63], off offset:192
	global_load_dwordx4 v[220:223], v[64:65], off offset:192
	global_load_dwordx4 v[224:227], v[66:67], off offset:192
	global_load_dwordx4 v[228:231], v[56:57], off offset:256
	global_load_dwordx4 v[232:235], v[58:59], off offset:256
	global_load_dwordx4 v[236:239], v[60:61], off offset:256
	global_load_dwordx4 v[240:243], v[62:63], off offset:256
	global_load_dwordx4 v[244:247], v[64:65], off offset:256
	global_load_dwordx4 v[248:251], v[66:67], off offset:256
	s_waitcnt vmcnt(24)
	ds_write_b128 v36, v[116:119] offset:0
	ds_write_b128 v36, v[120:123] offset:1024
	ds_write_b128 v36, v[124:127] offset:2048
	ds_write_b128 v36, v[128:131] offset:3072
	ds_write_b128 v36, v[132:135] offset:4096
	ds_write_b128 v36, v[136:139] offset:5120
	ds_read_b128 v[68:71], v37 offset:0
	ds_read_b128 v[72:75], v37 offset:1024
	ds_read_b128 v[76:79], v37 offset:2048
	ds_read_b128 v[80:83], v37 offset:3072
	ds_read_b128 v[84:87], v37 offset:4096
	ds_read_b128 v[88:91], v37 offset:5120
	s_waitcnt vmcnt(18)
	ds_write_b128 v36, v[140:143] offset:6144
	ds_write_b128 v36, v[144:147] offset:7168
	ds_write_b128 v36, v[148:151] offset:8192
	ds_write_b128 v36, v[152:155] offset:9216
	ds_write_b128 v36, v[156:159] offset:10240
	ds_write_b128 v36, v[168:171] offset:11264
	ds_read_b128 v[92:95], v37 offset:6144
	ds_read_b128 v[96:99], v37 offset:7168
	ds_read_b128 v[100:103], v37 offset:8192
	ds_read_b128 v[104:107], v37 offset:9216
	ds_read_b128 v[108:111], v37 offset:10240
	ds_read_b128 v[112:115], v37 offset:11264
	s_waitcnt lgkmcnt(12)
	global_load_dwordx4 v[116:119], v[56:57], off offset:320
	global_load_dwordx4 v[120:123], v[58:59], off offset:320
	global_load_dwordx4 v[124:127], v[60:61], off offset:320
	global_load_dwordx4 v[128:131], v[62:63], off offset:320
	global_load_dwordx4 v[132:135], v[64:65], off offset:320
	global_load_dwordx4 v[136:139], v[66:67], off offset:320
	v_mfma_f32_16x16x32_bf16 v[40:43], v[68:71], v[76:79], 0
	v_mfma_f32_16x16x32_bf16 v[44:47], v[68:71], v[80:83], 0
	v_mfma_f32_16x16x32_bf16 v[48:51], v[68:71], v[84:87], 0
	v_mfma_f32_16x16x32_bf16 v[24:27], v[68:71], v[88:91], 0
	v_mfma_f32_16x16x32_bf16 v[12:15], v[72:75], v[76:79], 0
	v_mfma_f32_16x16x32_bf16 v[16:19], v[72:75], v[80:83], 0
	v_mfma_f32_16x16x32_bf16 v[28:31], v[72:75], v[84:87], 0
	v_mfma_f32_16x16x32_bf16 v[0:3], v[72:75], v[88:91], 0
	s_waitcnt vmcnt(18)
	ds_write_b128 v36, v[172:175] offset:0
	ds_write_b128 v36, v[176:179] offset:1024
	ds_write_b128 v36, v[180:183] offset:2048
	ds_write_b128 v36, v[192:195] offset:3072
	ds_write_b128 v36, v[196:199] offset:4096
	ds_write_b128 v36, v[200:203] offset:5120
	ds_read_b128 v[68:71], v37 offset:0
	ds_read_b128 v[72:75], v37 offset:1024
	ds_read_b128 v[76:79], v37 offset:2048
	ds_read_b128 v[80:83], v37 offset:3072
	ds_read_b128 v[84:87], v37 offset:4096
	ds_read_b128 v[88:91], v37 offset:5120
	s_waitcnt lgkmcnt(12)
; #define MFMA16(a, b, c) __builtin_amdgcn_mfma_f32_16x16x32_bf16((a), (b), (c), 0, 0, 0)
; __device__ __forceinline__ void sk_tile(LAS unsigned char* lds, const bf16* A, int lda, const bf16* Wt, int K, int r0, int c0, int tid, int wave, int lane) {
;     ...
; #pragma unroll 2
;     for (int ks = 0; ks < (ksl >> 5); ++ks) {
;         bf16x8 af[2], bf[4];
; #pragma unroll
;         for (int m = 0; m < 2; ++m) af[m] = *(const bf16x8*)(ap + (size_t)(16 * m) * lda + 32 * ks);
; #pragma unroll
;         for (int j = 0; j < 4; ++j) bf[j] = *(const bf16x8*)(bp + (size_t)(16 * j) * K + 32 * ks);
; #pragma unroll
;         for (int m = 0; m < 2; ++m)
; #pragma unroll
;             for (int j = 0; j < 4; ++j) acc[m][j] = MFMA16(af[m], bf[j], acc[m][j]);
;     }
	global_load_dwordx4 v[140:143], v[56:57], off offset:384
	global_load_dwordx4 v[144:147], v[58:59], off offset:384
	global_load_dwordx4 v[148:151], v[60:61], off offset:384
	global_load_dwordx4 v[152:155], v[62:63], off offset:384
	global_load_dwordx4 v[156:159], v[64:65], off offset:384
	global_load_dwordx4 v[168:171], v[66:67], off offset:384
	v_mfma_f32_16x16x32_bf16 v[40:43], v[92:95], v[100:103], v[40:43]
	v_mfma_f32_16x16x32_bf16 v[44:47], v[92:95], v[104:107], v[44:47]
	v_mfma_f32_16x16x32_bf16 v[48:51], v[92:95], v[108:111], v[48:51]
	v_mfma_f32_16x16x32_bf16 v[24:27], v[92:95], v[112:115], v[24:27]
	v_mfma_f32_16x16x32_bf16 v[12:15], v[96:99], v[100:103], v[12:15]
	v_mfma_f32_16x16x32_bf16 v[16:19], v[96:99], v[104:107], v[16:19]
	v_mfma_f32_16x16x32_bf16 v[28:31], v[96:99], v[108:111], v[28:31]
	v_mfma_f32_16x16x32_bf16 v[0:3], v[96:99], v[112:115], v[0:3]
	s_waitcnt vmcnt(18)
	ds_write_b128 v36, v[204:207] offset:6144
	ds_write_b128 v36, v[208:211] offset:7168
	ds_write_b128 v36, v[212:215] offset:8192
	ds_write_b128 v36, v[216:219] offset:9216
	ds_write_b128 v36, v[220:223] offset:10240
	ds_write_b128 v36, v[224:227] offset:11264
	ds_read_b128 v[92:95], v37 offset:6144
	ds_read_b128 v[96:99], v37 offset:7168
	ds_read_b128 v[100:103], v37 offset:8192
	ds_read_b128 v[104:107], v37 offset:9216
	ds_read_b128 v[108:111], v37 offset:10240
	ds_read_b128 v[112:115], v37 offset:11264
	s_waitcnt lgkmcnt(12)
	global_load_dwordx4 v[172:175], v[56:57], off offset:448
	global_load_dwordx4 v[176:179], v[58:59], off offset:448
	global_load_dwordx4 v[180:183], v[60:61], off offset:448
	global_load_dwordx4 v[192:195], v[62:63], off offset:448
	global_load_dwordx4 v[196:199], v[64:65], off offset:448
	global_load_dwordx4 v[200:203], v[66:67], off offset:448
	v_mfma_f32_16x16x32_bf16 v[40:43], v[68:71], v[76:79], v[40:43]
	v_mfma_f32_16x16x32_bf16 v[44:47], v[68:71], v[80:83], v[44:47]
	v_mfma_f32_16x16x32_bf16 v[48:51], v[68:71], v[84:87], v[48:51]
	v_mfma_f32_16x16x32_bf16 v[24:27], v[68:71], v[88:91], v[24:27]
	v_mfma_f32_16x16x32_bf16 v[12:15], v[72:75], v[76:79], v[12:15]
	v_mfma_f32_16x16x32_bf16 v[16:19], v[72:75], v[80:83], v[16:19]
	v_mfma_f32_16x16x32_bf16 v[28:31], v[72:75], v[84:87], v[28:31]
	v_mfma_f32_16x16x32_bf16 v[0:3], v[72:75], v[88:91], v[0:3]
	s_waitcnt vmcnt(18)
	ds_write_b128 v36, v[228:231] offset:0
	ds_write_b128 v36, v[232:235] offset:1024
	ds_write_b128 v36, v[236:239] offset:2048
	ds_write_b128 v36, v[240:243] offset:3072
	ds_write_b128 v36, v[244:247] offset:4096
	ds_write_b128 v36, v[248:251] offset:5120
	ds_read_b128 v[68:71], v37 offset:0
	ds_read_b128 v[72:75], v37 offset:1024
	ds_read_b128 v[76:79], v37 offset:2048
	ds_read_b128 v[80:83], v37 offset:3072
	ds_read_b128 v[84:87], v37 offset:4096
	ds_read_b128 v[88:91], v37 offset:5120
	s_waitcnt lgkmcnt(12)
	global_load_dwordx4 v[204:207], v[56:57], off offset:512
	global_load_dwordx4 v[208:211], v[58:59], off offset:512
	global_load_dwordx4 v[212:215], v[60:61], off offset:512
	global_load_dwordx4 v[216:219], v[62:63], off offset:512
	global_load_dwordx4 v[220:223], v[64:65], off offset:512
	global_load_dwordx4 v[224:227], v[66:67], off offset:512
	v_mfma_f32_16x16x32_bf16 v[40:43], v[92:95], v[100:103], v[40:43]
	v_mfma_f32_16x16x32_bf16 v[44:47], v[92:95], v[104:107], v[44:47]
	v_mfma_f32_16x16x32_bf16 v[48:51], v[92:95], v[108:111], v[48:51]
	v_mfma_f32_16x16x32_bf16 v[24:27], v[92:95], v[112:115], v[24:27]
	v_mfma_f32_16x16x32_bf16 v[12:15], v[96:99], v[100:103], v[12:15]
	v_mfma_f32_16x16x32_bf16 v[16:19], v[96:99], v[104:107], v[16:19]
	v_mfma_f32_16x16x32_bf16 v[28:31], v[96:99], v[108:111], v[28:31]
	v_mfma_f32_16x16x32_bf16 v[0:3], v[96:99], v[112:115], v[0:3]
	s_waitcnt vmcnt(18)
	ds_write_b128 v36, v[116:119] offset:6144
	ds_write_b128 v36, v[120:123] offset:7168
	ds_write_b128 v36, v[124:127] offset:8192
	ds_write_b128 v36, v[128:131] offset:9216
	ds_write_b128 v36, v[132:135] offset:10240
	ds_write_b128 v36, v[136:139] offset:11264
	ds_read_b128 v[92:95], v37 offset:6144
	ds_read_b128 v[96:99], v37 offset:7168
	ds_read_b128 v[100:103], v37 offset:8192
	ds_read_b128 v[104:107], v37 offset:9216
	ds_read_b128 v[108:111], v37 offset:10240
	ds_read_b128 v[112:115], v37 offset:11264
	s_waitcnt lgkmcnt(12)
	global_load_dwordx4 v[228:231], v[56:57], off offset:576
	global_load_dwordx4 v[232:235], v[58:59], off offset:576
	global_load_dwordx4 v[236:239], v[60:61], off offset:576
	global_load_dwordx4 v[240:243], v[62:63], off offset:576
	global_load_dwordx4 v[244:247], v[64:65], off offset:576
	global_load_dwordx4 v[248:251], v[66:67], off offset:576
	v_mfma_f32_16x16x32_bf16 v[40:43], v[68:71], v[76:79], v[40:43]
	v_mfma_f32_16x16x32_bf16 v[44:47], v[68:71], v[80:83], v[44:47]
	v_mfma_f32_16x16x32_bf16 v[48:51], v[68:71], v[84:87], v[48:51]
	v_mfma_f32_16x16x32_bf16 v[24:27], v[68:71], v[88:91], v[24:27]
	v_mfma_f32_16x16x32_bf16 v[12:15], v[72:75], v[76:79], v[12:15]
	v_mfma_f32_16x16x32_bf16 v[16:19], v[72:75], v[80:83], v[16:19]
	v_mfma_f32_16x16x32_bf16 v[28:31], v[72:75], v[84:87], v[28:31]
	v_mfma_f32_16x16x32_bf16 v[0:3], v[72:75], v[88:91], v[0:3]
	s_waitcnt vmcnt(18)
	ds_write_b128 v36, v[140:143] offset:0
	ds_write_b128 v36, v[144:147] offset:1024
	ds_write_b128 v36, v[148:151] offset:2048
	ds_write_b128 v36, v[152:155] offset:3072
	ds_write_b128 v36, v[156:159] offset:4096
	ds_write_b128 v36, v[168:171] offset:5120
	ds_read_b128 v[68:71], v37 offset:0
	ds_read_b128 v[72:75], v37 offset:1024
	ds_read_b128 v[76:79], v37 offset:2048
	ds_read_b128 v[80:83], v37 offset:3072
	ds_read_b128 v[84:87], v37 offset:4096
	ds_read_b128 v[88:91], v37 offset:5120
	s_waitcnt lgkmcnt(12)
; #define LAS __attribute__((address_space(3)))
; #define MFMA16(a, b, c) __builtin_amdgcn_mfma_f32_16x16x32_bf16((a), (b), (c), 0, 0, 0)
; __device__ __forceinline__ void sk_tile(LAS unsigned char* lds, const bf16* A, int lda, const bf16* Wt, int K, int r0, int c0, int tid, int wave, int lane) {
;     ...
; #pragma unroll 2
;     for (int ks = 0; ks < (ksl >> 5); ++ks) {
;         bf16x8 af[2], bf[4];
; #pragma unroll
;         for (int m = 0; m < 2; ++m) af[m] = *(const bf16x8*)(ap + (size_t)(16 * m) * lda + 32 * ks);
; #pragma unroll
;         for (int j = 0; j < 4; ++j) bf[j] = *(const bf16x8*)(bp + (size_t)(16 * j) * K + 32 * ks);
; #pragma unroll
;         for (int m = 0; m < 2; ++m)
; #pragma unroll
;             for (int j = 0; j < 4; ++j) acc[m][j] = MFMA16(af[m], bf[j], acc[m][j]);
;     }
;     LAS float* part = (LAS float*)lds + wave * 2048;
; #pragma unroll
;     for (int m = 0; m < 2; ++m)
; #pragma unroll
;         for (int j = 0; j < 4; ++j)
; #pragma unroll
;             for (int e = 0; e < 4; ++e) part[(16 * m + 4 * kg + e) * 64 + 16 * j + r16] = acc[m][j][e];
;     __syncthreads();
	global_load_dwordx4 v[116:119], v[56:57], off offset:640
	global_load_dwordx4 v[120:123], v[58:59], off offset:640
	global_load_dwordx4 v[124:127], v[60:61], off offset:640
	global_load_dwordx4 v[128:131], v[62:63], off offset:640
	global_load_dwordx4 v[132:135], v[64:65], off offset:640
	global_load_dwordx4 v[136:139], v[66:67], off offset:640
	v_mfma_f32_16x16x32_bf16 v[40:43], v[92:95], v[100:103], v[40:43]
	v_mfma_f32_16x16x32_bf16 v[44:47], v[92:95], v[104:107], v[44:47]
	v_mfma_f32_16x16x32_bf16 v[48:51], v[92:95], v[108:111], v[48:51]
	v_mfma_f32_16x16x32_bf16 v[24:27], v[92:95], v[112:115], v[24:27]
	v_mfma_f32_16x16x32_bf16 v[12:15], v[96:99], v[100:103], v[12:15]
	v_mfma_f32_16x16x32_bf16 v[16:19], v[96:99], v[104:107], v[16:19]
	v_mfma_f32_16x16x32_bf16 v[28:31], v[96:99], v[108:111], v[28:31]
	v_mfma_f32_16x16x32_bf16 v[0:3], v[96:99], v[112:115], v[0:3]
	s_waitcnt vmcnt(18)
	ds_write_b128 v36, v[172:175] offset:6144
	ds_write_b128 v36, v[176:179] offset:7168
	ds_write_b128 v36, v[180:183] offset:8192
	ds_write_b128 v36, v[192:195] offset:9216
	ds_write_b128 v36, v[196:199] offset:10240
	ds_write_b128 v36, v[200:203] offset:11264
	ds_read_b128 v[92:95], v37 offset:6144
	ds_read_b128 v[96:99], v37 offset:7168
	ds_read_b128 v[100:103], v37 offset:8192
	ds_read_b128 v[104:107], v37 offset:9216
	ds_read_b128 v[108:111], v37 offset:10240
	ds_read_b128 v[112:115], v37 offset:11264
	s_waitcnt lgkmcnt(12)
	v_mfma_f32_16x16x32_bf16 v[40:43], v[68:71], v[76:79], v[40:43]
	v_mfma_f32_16x16x32_bf16 v[44:47], v[68:71], v[80:83], v[44:47]
	v_mfma_f32_16x16x32_bf16 v[48:51], v[68:71], v[84:87], v[48:51]
	v_mfma_f32_16x16x32_bf16 v[24:27], v[68:71], v[88:91], v[24:27]
	v_mfma_f32_16x16x32_bf16 v[12:15], v[72:75], v[76:79], v[12:15]
	v_mfma_f32_16x16x32_bf16 v[16:19], v[72:75], v[80:83], v[16:19]
	v_mfma_f32_16x16x32_bf16 v[28:31], v[72:75], v[84:87], v[28:31]
	v_mfma_f32_16x16x32_bf16 v[0:3], v[72:75], v[88:91], v[0:3]
	s_waitcnt vmcnt(12)
	ds_write_b128 v36, v[204:207] offset:0
	ds_write_b128 v36, v[208:211] offset:1024
	ds_write_b128 v36, v[212:215] offset:2048
	ds_write_b128 v36, v[216:219] offset:3072
	ds_write_b128 v36, v[220:223] offset:4096
	ds_write_b128 v36, v[224:227] offset:5120
	ds_read_b128 v[68:71], v37 offset:0
	ds_read_b128 v[72:75], v37 offset:1024
	ds_read_b128 v[76:79], v37 offset:2048
	ds_read_b128 v[80:83], v37 offset:3072
	ds_read_b128 v[84:87], v37 offset:4096
	ds_read_b128 v[88:91], v37 offset:5120
	s_waitcnt lgkmcnt(12)
	v_mfma_f32_16x16x32_bf16 v[40:43], v[92:95], v[100:103], v[40:43]
	v_mfma_f32_16x16x32_bf16 v[44:47], v[92:95], v[104:107], v[44:47]
	v_mfma_f32_16x16x32_bf16 v[48:51], v[92:95], v[108:111], v[48:51]
	v_mfma_f32_16x16x32_bf16 v[24:27], v[92:95], v[112:115], v[24:27]
	v_mfma_f32_16x16x32_bf16 v[12:15], v[96:99], v[100:103], v[12:15]
	v_mfma_f32_16x16x32_bf16 v[16:19], v[96:99], v[104:107], v[16:19]
	v_mfma_f32_16x16x32_bf16 v[28:31], v[96:99], v[108:111], v[28:31]
	v_mfma_f32_16x16x32_bf16 v[0:3], v[96:99], v[112:115], v[0:3]
	s_waitcnt vmcnt(6)
	ds_write_b128 v36, v[228:231] offset:6144
	ds_write_b128 v36, v[232:235] offset:7168
	ds_write_b128 v36, v[236:239] offset:8192
	ds_write_b128 v36, v[240:243] offset:9216
	ds_write_b128 v36, v[244:247] offset:10240
	ds_write_b128 v36, v[248:251] offset:11264
	ds_read_b128 v[92:95], v37 offset:6144
	ds_read_b128 v[96:99], v37 offset:7168
	ds_read_b128 v[100:103], v37 offset:8192
	ds_read_b128 v[104:107], v37 offset:9216
	ds_read_b128 v[108:111], v37 offset:10240
	ds_read_b128 v[112:115], v37 offset:11264
	s_waitcnt lgkmcnt(12)
	v_mfma_f32_16x16x32_bf16 v[40:43], v[68:71], v[76:79], v[40:43]
	v_mfma_f32_16x16x32_bf16 v[44:47], v[68:71], v[80:83], v[44:47]
	v_mfma_f32_16x16x32_bf16 v[48:51], v[68:71], v[84:87], v[48:51]
	v_mfma_f32_16x16x32_bf16 v[24:27], v[68:71], v[88:91], v[24:27]
	v_mfma_f32_16x16x32_bf16 v[12:15], v[72:75], v[76:79], v[12:15]
	v_mfma_f32_16x16x32_bf16 v[16:19], v[72:75], v[80:83], v[16:19]
	v_mfma_f32_16x16x32_bf16 v[28:31], v[72:75], v[84:87], v[28:31]
	v_mfma_f32_16x16x32_bf16 v[0:3], v[72:75], v[88:91], v[0:3]
	s_waitcnt vmcnt(0)
	ds_write_b128 v36, v[116:119] offset:0
	ds_write_b128 v36, v[120:123] offset:1024
	ds_write_b128 v36, v[124:127] offset:2048
	ds_write_b128 v36, v[128:131] offset:3072
	ds_write_b128 v36, v[132:135] offset:4096
	ds_write_b128 v36, v[136:139] offset:5120
	ds_read_b128 v[68:71], v37 offset:0
	ds_read_b128 v[72:75], v37 offset:1024
	ds_read_b128 v[76:79], v37 offset:2048
	ds_read_b128 v[80:83], v37 offset:3072
	ds_read_b128 v[84:87], v37 offset:4096
	ds_read_b128 v[88:91], v37 offset:5120
	s_waitcnt lgkmcnt(12)
	v_mfma_f32_16x16x32_bf16 v[40:43], v[92:95], v[100:103], v[40:43]
	v_mfma_f32_16x16x32_bf16 v[44:47], v[92:95], v[104:107], v[44:47]
	v_mfma_f32_16x16x32_bf16 v[48:51], v[92:95], v[108:111], v[48:51]
	v_mfma_f32_16x16x32_bf16 v[24:27], v[92:95], v[112:115], v[24:27]
	v_mfma_f32_16x16x32_bf16 v[12:15], v[96:99], v[100:103], v[12:15]
	v_mfma_f32_16x16x32_bf16 v[16:19], v[96:99], v[104:107], v[16:19]
	v_mfma_f32_16x16x32_bf16 v[28:31], v[96:99], v[108:111], v[28:31]
	v_mfma_f32_16x16x32_bf16 v[0:3], v[96:99], v[112:115], v[0:3]
	s_waitcnt lgkmcnt(0)
	v_mfma_f32_16x16x32_bf16 v[40:43], v[68:71], v[76:79], v[40:43]
	v_mfma_f32_16x16x32_bf16 v[44:47], v[68:71], v[80:83], v[44:47]
	v_mfma_f32_16x16x32_bf16 v[48:51], v[68:71], v[84:87], v[48:51]
	v_mfma_f32_16x16x32_bf16 v[24:27], v[68:71], v[88:91], v[24:27]
	v_mfma_f32_16x16x32_bf16 v[12:15], v[72:75], v[76:79], v[12:15]
	v_mfma_f32_16x16x32_bf16 v[16:19], v[72:75], v[80:83], v[16:19]
	v_mfma_f32_16x16x32_bf16 v[28:31], v[72:75], v[84:87], v[28:31]
	v_mfma_f32_16x16x32_bf16 v[0:3], v[72:75], v[88:91], v[0:3]
	s_nop 7
	s_nop 1
	s_barrier
; #define LAS __attribute__((address_space(3)))
; __device__ __forceinline__ unsigned long long rt() { return __builtin_amdgcn_s_memrealtime(); }
; __device__ __forceinline__ unsigned cvtpk(float lo, float hi) { f32x2_t v = {lo, hi}; bf16x2_t b = __builtin_convertvector(v, bf16x2_t); return __builtin_bit_cast(unsigned, b); }
; __device__ __forceinline__ void sk_tile(LAS unsigned char* lds, const bf16* A, int lda, const bf16* Wt, int K, int r0, int c0, int tid, int wave, int lane) {
;     ...
;     LAS float* part = (LAS float*)lds + wave * 2048;
; #pragma unroll
;     for (int m = 0; m < 2; ++m)
; #pragma unroll
;         for (int j = 0; j < 4; ++j)
; #pragma unroll
;             for (int e = 0; e < 4; ++e) part[(16 * m + 4 * kg + e) * 64 + 16 * j + r16] = acc[m][j][e];
;     __syncthreads();
;     {
;         const LAS f32x4* p4 = (const LAS f32x4*)lds + tid;
;         f32x4 s = p4[0];
; #pragma unroll
;         for (int w = 1; w < 8; ++w) s += p4[w * 512];
;         ((LAS f32x4*)(lds + 65536))[tid] = s;
;     }
;     __syncthreads();
; }
; __device__ __forceinline__ void sk_gemm_y(LAS unsigned char* lds, const bf16* A, int lda, const bf16* Wt, int K, bf16* Y, int tid, int wave, int lane) {
;     for (int item = blockIdx.x; item < 256; item += gridDim.x) {
;         const int rt = item >> 4, ct = item & 15;
;         sk_tile(lds, A, lda, Wt, K, MP + 32 * rt, 64 * ct, tid, wave, lane);
;         const f32x4 v = ((const LAS f32x4*)(lds + 65536))[tid];
;         *(uint2*)(Y + (size_t)(MP + 32 * rt + (tid >> 4)) * D + 64 * ct + 4 * (tid & 15)) = make_uint2(cvtpk(v[0], v[1]), cvtpk(v[2], v[3]));
;         __syncthreads();
	ds_write2_b32 v22, v40, v44 offset1:16
	ds_write2_b32 v22, v41, v45 offset0:64 offset1:80
	ds_write2_b32 v22, v42, v46 offset0:128 offset1:144
	ds_write2_b32 v22, v43, v47 offset0:192 offset1:208
	ds_write2_b32 v22, v48, v24 offset0:32 offset1:48
	ds_write2_b32 v22, v49, v25 offset0:96 offset1:112
	ds_write2_b32 v22, v50, v26 offset0:160 offset1:176
	ds_write2_b32 v22, v51, v27 offset0:224 offset1:240
	ds_write2_b32 v23, v12, v16 offset1:16
	ds_write2_b32 v23, v13, v17 offset0:64 offset1:80
	ds_write2_b32 v23, v14, v18 offset0:128 offset1:144
	ds_write2_b32 v23, v15, v19 offset0:192 offset1:208
	ds_write2_b32 v23, v28, v0 offset0:32 offset1:48
	ds_write2_b32 v23, v29, v1 offset0:96 offset1:112
	ds_write2_b32 v23, v30, v2 offset0:160 offset1:176
	ds_write2_b32 v23, v31, v3 offset0:224 offset1:240
	s_waitcnt lgkmcnt(0)
	s_barrier
	ds_read_b128 v[0:3], v20
	ds_read_b128 v[12:15], v20 offset:8192
	ds_read_b128 v[16:19], v20 offset:16384
	ds_read_b128 v[24:27], v20 offset:24576
	ds_read_b128 v[28:31], v20 offset:32768
	ds_read_b128 v[32:35], v20 offset:40960
	ds_read_b128 v[36:39], v20 offset:49152
	ds_read_b128 v[40:43], v20 offset:57344
	s_waitcnt lgkmcnt(6)
	v_pk_add_f32 v[2:3], v[2:3], v[14:15]
	v_pk_add_f32 v[0:1], v[0:1], v[12:13]
	s_waitcnt lgkmcnt(5)
	v_pk_add_f32 v[2:3], v[2:3], v[18:19]
	v_pk_add_f32 v[0:1], v[0:1], v[16:17]
	s_waitcnt lgkmcnt(4)
	v_pk_add_f32 v[2:3], v[2:3], v[26:27]
	v_pk_add_f32 v[0:1], v[0:1], v[24:25]
	s_waitcnt lgkmcnt(3)
	v_pk_add_f32 v[2:3], v[2:3], v[30:31]
	v_pk_add_f32 v[0:1], v[0:1], v[28:29]
	s_waitcnt lgkmcnt(2)
	v_pk_add_f32 v[2:3], v[2:3], v[34:35]
	v_pk_add_f32 v[0:1], v[0:1], v[32:33]
	s_waitcnt lgkmcnt(1)
	v_pk_add_f32 v[2:3], v[2:3], v[38:39]
	v_pk_add_f32 v[0:1], v[0:1], v[36:37]
	s_waitcnt lgkmcnt(0)
	v_pk_add_f32 v[2:3], v[2:3], v[42:43]
	v_pk_add_f32 v[0:1], v[0:1], v[40:41]
	ds_write_b128 v21, v[0:3]
	s_waitcnt lgkmcnt(0)
	s_barrier
	ds_read_b128 v[0:3], v21
	s_waitcnt lgkmcnt(0)
	v_cvt_pk_bf16_f32 v0, v0, v1
	v_cvt_pk_bf16_f32 v1, v2, v3
	global_store_dwordx2 v[52:53], v[0:1], off
	s_barrier
	s_cbranch_scc1 .LBB0_1670
